# lever 4: v14 + one static s_setprio 1 for the younger half (wr==1 waves) at each GEMM prologue
# baseline (speedup 1.0000x reference)
; #define PG8_BAR __builtin_amdgcn_s_barrier()
;     __host__ __device__ bool next(int i, Unit& u) const {
;         const long L = (long)i * G + c; if (L >= nwg) return false;
;         int wgid = (int)L; { const int q = nwg / NXCD, r = nwg % NXCD, xcd = wgid % NXCD, off = wgid / NXCD; wgid = (xcd < r ? xcd * (q + 1) : r * (q + 1) + (xcd - r) * q) + off; }
;         const int nig = WGM * nN, gid = wgid / nig, fm = gid * WGM, gsz = (nM - fm) < WGM ? (nM - fm) : WGM;
;         u.pm = fm + ((wgid % nig) % gsz); u.pn = (wgid % nig) / gsz; return true;
; template <class Epi, class Sched, bool ALIGN_EPI = false, bool SP2 = false>
; __device__ __forceinline__ void gemm_phase(PG8_LAS unsigned char* lds, const Gemm g, const Sched& S, const Epi& E) {
;     const int tid = threadIdx.x, wid = __builtin_amdgcn_readfirstlane(tid >> 6), lane = tid & 63, wr = wid >> 2, wc = wid & 3, fr = lane & 15, fq = lane >> 4;
;     const int K = g.K, nt = K / BK;
;     unsigned voffA[2], voffB[2];
; #pragma unroll
;     for (int i = 0; i < 2; ++i) { int R, C; stage_rc(tid * 16 + i * 8192, R, C); const int Rb = Epi::PERM ? ((R & ~31) + perm32(R & 31)) : R;
;         voffA[i] = (unsigned)(R * 64 + C) * 2u; voffB[i] = (unsigned)(Rb * 64 + C) * 2u; }
;     const size_t kstep = (size_t)(BM * BK * 2);
;     const size_t hstep = (size_t)HALF * BK * 2;
;     const size_t tstep = (size_t)K * BM * 2;
;     const unsigned ldsw = (unsigned)wid * 1024u;
;     const int aoff = lds_byte(wr * 64 + fr, fq * 8), boff = lds_byte(wc * 32 + fr, fq * 8);
;     ...
;     Unit cur, nxt; int ui = 0;
;     if (!S.next(0, cur)) return;
;     f32x4 acc[2][2][4][2];
; #pragma unroll
;     for (int a = 0; a < 2; ++a)
; #pragma unroll
;         for (int b = 0; b < 2; ++b)
; #pragma unroll
;             for (int m = 0; m < 4; ++m)
; #pragma unroll
;                 for (int n = 0; n < 2; ++n) acc[a][b][m][n] = (f32x4){0.f, 0.f, 0.f, 0.f};
;     bf16x8 At[4][2], B0[2][2], B1[2][2];
;     const char* cA = (const char*)g.A + (size_t)cur.pm * tstep; const char* cB = (const char*)g.Bt + (size_t)cur.pn * tstep;
;     S.a_ready(cur);
;     if constexpr (SP2) {
;         PG8_STAGE(PG8_SB(0, 0), cB, voffB); PG8_STAGE(PG8_SB(0, 1), cB + hstep, voffB); PG8_STAGE(PG8_SA(0, 0), cA, voffA); PG8_STAGE(PG8_SA(0, 1), cA + hstep, voffA);
;         if (wr == 1) PG8_BAR;
.LBB0_105:
	s_cmp_lt_i32 s54, 2
	s_cselect_b64 s[6:7], -1, 0
	s_add_u32 s12, s52, 0xd400000
	s_addc_u32 s13, s53, 0
	s_add_u32 s20, s52, 0x34c00000
	s_addc_u32 s21, s53, 0
	s_and_b64 s[6:7], s[6:7], s[0:1]
	s_andn2_b64 vcc, exec, s[6:7]
	s_cbranch_vccnz .LBB0_130
	s_cmpk_gt_i32 s2, 0xabf
	v_readfirstlane_b32 s1, v0
	s_cbranch_scc1 .LBB0_122
	v_lshrrev_b32_e32 v6, 1, v0
	v_lshrrev_b32_e32 v7, 5, v0
	v_lshlrev_b32_e32 v4, 4, v0
	v_and_b32_e32 v1, 32, v0
	v_and_b32_e32 v6, 24, v6
	v_and_b32_e32 v7, 4, v7
	v_bfe_u32 v8, v0, 2, 2
	v_bfe_u32 v5, v0, 2, 4
	v_bitop3_b32 v2, v4, v1, 48 bitop3:0x6c
	v_and_b32_e32 v3, 64, v0
	v_or3_b32 v8, v7, v8, v6
	v_lshrrev_b32_e32 v7, 3, v0
	v_or_b32_e32 v1, v2, v3
	v_and_or_b32 v9, v7, 48, v5
	v_and_or_b32 v7, v7, 32, v8
	v_lshl_or_b32 v132, v7, 7, v1
	v_or_b32_e32 v7, 0x2000, v4
	v_lshl_or_b32 v130, v9, 7, v1
	v_lshrrev_b32_e32 v9, 7, v7
	s_movk_i32 s0, 0x70
	v_and_or_b32 v10, v9, s0, v5
	s_movk_i32 s0, 0x60
	s_ashr_i32 s26, s2, 31
	v_and_or_b32 v8, v9, s0, v8
	s_lshr_b32 s0, s26, 29
	s_add_i32 s0, s2, s0
	s_lshr_b32 s14, s1, 6
	s_ashr_i32 s10, s0, 3
	s_and_b32 s0, s0, -8
	s_lshr_b32 s15, s1, 8
	s_lshl_b32 s3, s14, 10
	s_sub_i32 s0, s2, s0
	s_cmp_lt_i32 s0, 0
	s_movk_i32 s27, 0x159
	s_cselect_b32 s11, s27, 0x158
	s_mul_i32 s0, s0, s11
	s_add_i32 s0, s0, s10
	s_mul_hi_i32 s10, s0, 0x2fa0be83
	s_lshr_b32 s11, s10, 31
	s_ashr_i32 s10, s10, 7
	s_add_i32 s10, s10, s11
	s_lshl_b32 s11, s10, 3
	s_mulk_i32 s10, 0x2b0
	s_sub_i32 s10, s0, s10
	s_sext_i32_i16 s0, s10
	s_bfe_u32 s0, s0, 0x3001c
	s_add_i32 s18, s10, s0
	s_sext_i32_i16 s0, s18
	s_and_b32 s18, s18, 0xfff8
	s_sub_i32 s10, s10, s18
	s_sext_i32_i16 s10, s10
	s_lshr_b32 s0, s0, 3
	s_add_i32 s46, s11, s10
	s_ashr_i32 s47, s46, 31
	s_bfe_i64 s[18:19], s[0:1], 0x100000
	s_lshl_b64 s[10:11], s[46:47], 21
	s_lshl_b64 s[18:19], s[18:19], 21
	s_add_u32 s50, s4, s18
	s_addc_u32 s51, s5, s19
	s_add_i32 s28, s3, 0
	s_add_i32 m0, s28, 0x10000
	v_lshl_or_b32 v136, v8, 7, v1
	global_load_lds_dwordx4 v132, s[50:51]
	s_add_i32 m0, s28, 0x12000
	s_add_u32 s18, s50, 0x4000
	global_load_lds_dwordx4 v136, s[50:51]
	s_addc_u32 s19, s51, 0
	s_add_i32 m0, s28, 0x14000
	v_lshl_or_b32 v134, v10, 7, v1
	global_load_lds_dwordx4 v132, s[18:19]
	s_add_i32 m0, s28, 0x16000
	s_add_u32 s48, s66, s10
	s_addc_u32 s49, s67, s11
	s_add_i32 s29, s28, 0x2000
	global_load_lds_dwordx4 v136, s[18:19]
	s_mov_b32 m0, s28
	s_add_u32 s10, s48, 0x4000
	global_load_lds_dwordx4 v130, s[48:49]
	s_mov_b32 m0, s29
	s_addc_u32 s11, s49, 0
	s_add_i32 s30, s28, 0x4000
	global_load_lds_dwordx4 v134, s[48:49]
	s_mov_b32 m0, s30
	s_add_i32 s31, s28, 0x6000
	global_load_lds_dwordx4 v130, s[10:11]
	s_mov_b32 m0, s31
	v_mov_b32_e32 v139, 0
	global_load_lds_dwordx4 v134, s[10:11]
	s_cmp_eq_u32 s15, 1
	v_mov_b32_e32 v133, v139
	v_mov_b32_e32 v137, v139
	v_mov_b32_e32 v131, v139
	v_mov_b32_e32 v135, v139
	s_cselect_b64 s[10:11], -1, 0
	s_cmp_lg_u32 s15, 1
	s_mov_b32 s33, 0
	s_cbranch_scc1 .LBB0_109
	s_setprio 1
	s_barrier

;     __device__ __forceinline__ bool next(int i, Unit& u) const { if (i >= 2) return false; const int xcd = c & 7, off = c >> 3; u.pm = 16 * i + 4 * (xcd >> 1) + (off & 3); u.pn = 8 * (xcd & 1) + (off >> 2); return true; }
; #define PG8_STAGE(bufoff, gbase, voff) do { _Pragma("unroll") for (int _i = 0; _i < 2; ++_i) \
;         __builtin_amdgcn_global_load_lds((const unsigned*)((const char*)(gbase) + (voff)[_i]), (PG8_LAS unsigned*)(lds + (bufoff) + ldsw + _i * 8192), 16, 0, 0); } while (0)
; #define PG8_BAR __builtin_amdgcn_s_barrier()
; template <class Epi, class Sched, bool ALIGN_EPI = false, bool SP2 = false>
; __device__ __forceinline__ void gemm_phase(PG8_LAS unsigned char* lds, const Gemm g, const Sched& S, const Epi& E) {
;     ...
;     for (int i = 0; i < 2; ++i) { int R, C; stage_rc(tid * 16 + i * 8192, R, C); const int Rb = Epi::PERM ? ((R & ~31) + perm32(R & 31)) : R;
;         voffA[i] = (unsigned)(R * 64 + C) * 2u; voffB[i] = (unsigned)(Rb * 64 + C) * 2u; }
;     const size_t kstep = (size_t)(BM * BK * 2);
;     const size_t hstep = (size_t)HALF * BK * 2;
;     const size_t tstep = (size_t)K * BM * 2;
;     const unsigned ldsw = (unsigned)wid * 1024u;
;     const int aoff = lds_byte(wr * 64 + fr, fq * 8), boff = lds_byte(wc * 32 + fr, fq * 8);
;     ...
;     Unit cur, nxt; int ui = 0;
;     if (!S.next(0, cur)) return;
;     f32x4 acc[2][2][4][2];
; #pragma unroll
;     for (int a = 0; a < 2; ++a)
; #pragma unroll
;         for (int b = 0; b < 2; ++b)
; #pragma unroll
;             for (int m = 0; m < 4; ++m)
; #pragma unroll
;                 for (int n = 0; n < 2; ++n) acc[a][b][m][n] = (f32x4){0.f, 0.f, 0.f, 0.f};
;     bf16x8 At[4][2], B0[2][2], B1[2][2];
;     const char* cA = (const char*)g.A + (size_t)cur.pm * tstep; const char* cB = (const char*)g.Bt + (size_t)cur.pn * tstep;
;     S.a_ready(cur);
;     if constexpr (SP2) {
;         PG8_STAGE(PG8_SB(0, 0), cB, voffB); PG8_STAGE(PG8_SB(0, 1), cB + hstep, voffB); PG8_STAGE(PG8_SA(0, 0), cA, voffA); PG8_STAGE(PG8_SA(0, 1), cA + hstep, voffA);
;         if (wr == 1) PG8_BAR;
.LBB0_183:
	s_andn2_b64 vcc, exec, s[0:1]
	s_cbranch_vccnz .LBB0_223
	v_lshrrev_b32_e32 v6, 1, v0
	v_lshrrev_b32_e32 v7, 5, v0
	v_lshlrev_b32_e32 v4, 4, v0
	v_and_b32_e32 v1, 32, v0
	v_and_b32_e32 v6, 24, v6
	v_and_b32_e32 v7, 4, v7
	v_bfe_u32 v8, v0, 2, 2
	v_bfe_u32 v5, v0, 2, 4
	v_bitop3_b32 v2, v4, v1, 48 bitop3:0x6c
	v_and_b32_e32 v3, 64, v0
	v_or3_b32 v7, v7, v8, v6
	v_lshrrev_b32_e32 v6, 3, v0
	v_or_b32_e32 v1, v2, v3
	v_and_or_b32 v8, v6, 48, v5
	v_and_or_b32 v6, v6, 32, v7
	v_lshl_or_b32 v132, v6, 7, v1
	v_or_b32_e32 v6, 0x2000, v4
	v_lshl_or_b32 v130, v8, 7, v1
	v_lshrrev_b32_e32 v8, 7, v6
	s_movk_i32 s0, 0x70
	v_and_or_b32 v9, v8, s0, v5
	s_movk_i32 s0, 0x60
	v_and_or_b32 v7, v8, s0, v7
	s_lshr_b32 s0, s4, 6
	s_lshr_b32 s1, s4, 8
	s_lshl_b32 s3, s0, 10
	s_mul_i32 s7, s72, 0x560000
	s_mul_hi_i32 s6, s72, 0x560000
	s_add_u32 s46, s12, s7
	s_addc_u32 s47, s13, s6
	s_add_i32 s26, s3, 0
	s_add_i32 m0, s26, 0x10000
	v_lshl_or_b32 v136, v7, 7, v1
	global_load_lds_dwordx4 v132, s[46:47]
	s_add_i32 m0, s26, 0x12000
	s_add_u32 s6, s46, 0x4000
	global_load_lds_dwordx4 v136, s[46:47]
	s_addc_u32 s7, s47, 0
	s_add_i32 m0, s26, 0x14000
	s_mul_i32 s16, s73, 0x560000
	global_load_lds_dwordx4 v132, s[6:7]
	s_add_i32 m0, s26, 0x16000
	s_mul_hi_i32 s5, s73, 0x560000
	s_add_u32 s44, s20, s16
	s_addc_u32 s45, s21, s5
	s_add_i32 s27, s26, 0x2000
	global_load_lds_dwordx4 v136, s[6:7]
	s_mov_b32 m0, s26
	s_add_u32 s6, s44, 0x4000
	v_lshl_or_b32 v134, v9, 7, v1
	global_load_lds_dwordx4 v130, s[44:45]
	s_mov_b32 m0, s27
	s_addc_u32 s7, s45, 0
	s_add_i32 s28, s26, 0x4000
	global_load_lds_dwordx4 v134, s[44:45]
	s_mov_b32 m0, s28
	s_add_i32 s29, s26, 0x6000
	global_load_lds_dwordx4 v130, s[6:7]
	s_mov_b32 m0, s29
	v_mov_b32_e32 v139, 0
	global_load_lds_dwordx4 v134, s[6:7]
	s_cmp_eq_u32 s1, 1
	v_mov_b32_e32 v133, v139
	v_mov_b32_e32 v137, v139
	v_mov_b32_e32 v131, v139
	v_mov_b32_e32 v135, v139
	s_cselect_b64 s[16:17], -1, 0
	s_cmp_lg_u32 s1, 1
	s_mov_b32 s30, 0
	s_cbranch_scc1 .LBB0_186
	s_setprio 1
	s_barrier

;     __device__ __forceinline__ bool next(int i, Unit& u) const { if (i >= 2) return false; const int xcd = c & 7, off = c >> 3; u.pm = 16 * i + 4 * (xcd >> 1) + (off & 3); u.pn = 8 * (xcd & 1) + (off >> 2); return true; }
; #define PG8_STAGE(bufoff, gbase, voff) do { _Pragma("unroll") for (int _i = 0; _i < 2; ++_i) \
;         __builtin_amdgcn_global_load_lds((const unsigned*)((const char*)(gbase) + (voff)[_i]), (PG8_LAS unsigned*)(lds + (bufoff) + ldsw + _i * 8192), 16, 0, 0); } while (0)
; #define PG8_BAR __builtin_amdgcn_s_barrier()
; template <class Epi, class Sched, bool ALIGN_EPI = false, bool SP2 = false>
; __device__ __forceinline__ void gemm_phase(PG8_LAS unsigned char* lds, const Gemm g, const Sched& S, const Epi& E) {
;     ...
;     for (int i = 0; i < 2; ++i) { int R, C; stage_rc(tid * 16 + i * 8192, R, C); const int Rb = Epi::PERM ? ((R & ~31) + perm32(R & 31)) : R;
;         voffA[i] = (unsigned)(R * 64 + C) * 2u; voffB[i] = (unsigned)(Rb * 64 + C) * 2u; }
;     const size_t kstep = (size_t)(BM * BK * 2);
;     const size_t hstep = (size_t)HALF * BK * 2;
;     const size_t tstep = (size_t)K * BM * 2;
;     const unsigned ldsw = (unsigned)wid * 1024u;
;     const int aoff = lds_byte(wr * 64 + fr, fq * 8), boff = lds_byte(wc * 32 + fr, fq * 8);
;     ...
;     Unit cur, nxt; int ui = 0;
;     if (!S.next(0, cur)) return;
;     f32x4 acc[2][2][4][2];
; #pragma unroll
;     for (int a = 0; a < 2; ++a)
; #pragma unroll
;         for (int b = 0; b < 2; ++b)
; #pragma unroll
;             for (int m = 0; m < 4; ++m)
; #pragma unroll
;                 for (int n = 0; n < 2; ++n) acc[a][b][m][n] = (f32x4){0.f, 0.f, 0.f, 0.f};
;     bf16x8 At[4][2], B0[2][2], B1[2][2];
;     const char* cA = (const char*)g.A + (size_t)cur.pm * tstep; const char* cB = (const char*)g.Bt + (size_t)cur.pn * tstep;
;     S.a_ready(cur);
;     if constexpr (SP2) {
;         PG8_STAGE(PG8_SB(0, 0), cB, voffB); PG8_STAGE(PG8_SB(0, 1), cB + hstep, voffB); PG8_STAGE(PG8_SA(0, 0), cA, voffA); PG8_STAGE(PG8_SA(0, 1), cA + hstep, voffA);
;         if (wr == 1) PG8_BAR;
.LBB0_281:
	s_andn2_b64 vcc, exec, s[0:1]
	s_cbranch_vccnz .LBB0_393
	v_lshrrev_b32_e32 v6, 5, v0
	v_lshlrev_b32_e32 v4, 4, v0
	v_and_b32_e32 v1, 32, v0
	v_and_b32_e32 v6, 4, v6
	v_bfe_u32 v7, v0, 2, 2
	v_bfe_u32 v5, v0, 2, 4
	v_bitop3_b32 v2, v4, v1, 48 bitop3:0x6c
	s_waitcnt lgkmcnt(0)
	v_and_b32_e32 v3, 64, v0
	v_or3_b32 v7, v6, v7, v20
	v_lshrrev_b32_e32 v6, 3, v0
	v_or_b32_e32 v1, v2, v3
	v_and_or_b32 v8, v6, 48, v5
	v_and_or_b32 v6, v6, 32, v7
	v_lshl_or_b32 v132, v6, 7, v1
	v_or_b32_e32 v6, 0x2000, v4
	v_lshl_or_b32 v130, v8, 7, v1
	v_lshrrev_b32_e32 v8, 7, v6
	s_movk_i32 s5, 0x70
	v_and_or_b32 v9, v8, s5, v5
	s_movk_i32 s5, 0x60
	s_lshr_b32 s1, s12, 6
	v_and_or_b32 v7, v8, s5, v7
	s_ashr_i32 s5, s4, 31
	s_ashr_i32 s51, s50, 31
	s_lshr_b32 s0, s12, 8
	s_lshl_b32 s3, s1, 10
	s_lshl_b64 s[8:9], s[4:5], 21
	s_lshl_b64 s[14:15], s[50:51], 21
	s_add_u32 s74, s70, s14
	s_addc_u32 s75, s71, s15
	s_add_i32 s15, s3, 0
	s_add_i32 m0, s15, 0x10000
	v_lshl_or_b32 v136, v7, 7, v1
	global_load_lds_dwordx4 v132, s[74:75]
	s_add_i32 m0, s15, 0x12000
	s_add_u32 s16, s74, 0x4000
	global_load_lds_dwordx4 v136, s[74:75]
	s_addc_u32 s17, s75, 0
	s_add_i32 m0, s15, 0x14000
	v_lshl_or_b32 v134, v9, 7, v1
	global_load_lds_dwordx4 v132, s[16:17]
	s_add_i32 m0, s15, 0x16000
	s_add_u32 s72, s42, s8
	s_addc_u32 s73, s43, s9
	s_add_i32 s27, s15, 0x2000
	global_load_lds_dwordx4 v136, s[16:17]
	s_mov_b32 m0, s15
	s_add_u32 s8, s72, 0x4000
	global_load_lds_dwordx4 v130, s[72:73]
	s_mov_b32 m0, s27
	s_addc_u32 s9, s73, 0
	s_add_i32 s28, s15, 0x4000
	global_load_lds_dwordx4 v134, s[72:73]
	s_mov_b32 m0, s28
	s_add_i32 s29, s15, 0x6000
	global_load_lds_dwordx4 v130, s[8:9]
	s_mov_b32 m0, s29
	v_mov_b32_e32 v133, 0
	global_load_lds_dwordx4 v134, s[8:9]
	s_cmp_eq_u32 s0, 1
	v_mov_b32_e32 v137, v133
	v_mov_b32_e32 v131, v133
	v_mov_b32_e32 v135, v133
	s_cselect_b64 s[8:9], -1, 0
	s_cmp_lg_u32 s0, 1
	s_mov_b32 s30, 0
	s_cbranch_scc1 .LBB0_284
	s_setprio 1
	s_barrier

; #define PG8_BAR __builtin_amdgcn_s_barrier()
;     __host__ __device__ bool next(int i, Unit& u) const {
;         const long L = (long)i * G + c; if (L >= nwg) return false;
;         int wgid = (int)L; { const int q = nwg / NXCD, r = nwg % NXCD, xcd = wgid % NXCD, off = wgid / NXCD; wgid = (xcd < r ? xcd * (q + 1) : r * (q + 1) + (xcd - r) * q) + off; }
;         const int nig = WGM * nN, gid = wgid / nig, fm = gid * WGM, gsz = (nM - fm) < WGM ? (nM - fm) : WGM;
;         u.pm = fm + ((wgid % nig) % gsz); u.pn = (wgid % nig) / gsz; return true;
; template <class Epi, class Sched, bool ALIGN_EPI = false, bool SP2 = false>
; __device__ __forceinline__ void gemm_phase(PG8_LAS unsigned char* lds, const Gemm g, const Sched& S, const Epi& E) {
;     const int tid = threadIdx.x, wid = __builtin_amdgcn_readfirstlane(tid >> 6), lane = tid & 63, wr = wid >> 2, wc = wid & 3, fr = lane & 15, fq = lane >> 4;
;     const int K = g.K, nt = K / BK;
;     unsigned voffA[2], voffB[2];
; #pragma unroll
;     for (int i = 0; i < 2; ++i) { int R, C; stage_rc(tid * 16 + i * 8192, R, C); const int Rb = Epi::PERM ? ((R & ~31) + perm32(R & 31)) : R;
;         voffA[i] = (unsigned)(R * 64 + C) * 2u; voffB[i] = (unsigned)(Rb * 64 + C) * 2u; }
;     const size_t kstep = (size_t)(BM * BK * 2);
;     const size_t hstep = (size_t)HALF * BK * 2;
;     const size_t tstep = (size_t)K * BM * 2;
;     const unsigned ldsw = (unsigned)wid * 1024u;
;     const int aoff = lds_byte(wr * 64 + fr, fq * 8), boff = lds_byte(wc * 32 + fr, fq * 8);
;     ...
;     Unit cur, nxt; int ui = 0;
;     if (!S.next(0, cur)) return;
;     f32x4 acc[2][2][4][2];
; #pragma unroll
;     for (int a = 0; a < 2; ++a)
; #pragma unroll
;         for (int b = 0; b < 2; ++b)
; #pragma unroll
;             for (int m = 0; m < 4; ++m)
; #pragma unroll
;                 for (int n = 0; n < 2; ++n) acc[a][b][m][n] = (f32x4){0.f, 0.f, 0.f, 0.f};
;     bf16x8 At[4][2], B0[2][2], B1[2][2];
;     const char* cA = (const char*)g.A + (size_t)cur.pm * tstep; const char* cB = (const char*)g.Bt + (size_t)cur.pn * tstep;
;     S.a_ready(cur);
;     if constexpr (SP2) {
;         PG8_STAGE(PG8_SB(0, 0), cB, voffB); PG8_STAGE(PG8_SB(0, 1), cB + hstep, voffB); PG8_STAGE(PG8_SA(0, 0), cA, voffA); PG8_STAGE(PG8_SA(0, 1), cA + hstep, voffA);
;         if (wr == 1) PG8_BAR;
.LBB0_670:
	v_lshlrev_b32_e32 v6, 4, v0
	v_and_b32_e32 v1, 32, v0
	v_lshrrev_b32_e32 v4, 5, v0
	s_ashr_i32 s0, s7, 3
	v_bfe_u32 v7, v0, 2, 4
	v_bitop3_b32 v2, v6, v1, 48 bitop3:0x6c
	v_and_b32_e32 v1, 24, v196
	v_and_b32_e32 v4, 4, v4
	v_bfe_u32 v5, v0, 2, 2
	v_lshrrev_b32_e32 v8, 3, v0
	s_waitcnt lgkmcnt(0)
	v_and_b32_e32 v3, 64, v0
	v_or3_b32 v12, v4, v5, v1
	v_and_or_b32 v9, v8, 48, v7
	v_and_b32_e32 v8, 32, v8
	s_add_i32 s0, s6, s0
	v_or_b32_e32 v11, v2, v3
	v_or_b32_e32 v10, v12, v8
	s_ashr_i32 s6, s0, 31
	v_lshl_or_b32 v136, v10, 7, v11
	v_or_b32_e32 v10, 0x2000, v6
	s_lshr_b32 s6, s6, 25
	v_lshl_or_b32 v134, v9, 7, v11
	v_lshrrev_b32_e32 v9, 7, v10
	s_movk_i32 s7, 0x70
	s_add_i32 s6, s0, s6
	v_and_or_b32 v13, v9, s7, v7
	s_ashr_i32 s7, s6, 7
	s_and_b32 s6, s6, 0xffffff80
	s_sub_i32 s6, s0, s6
	s_bfe_i32 s0, s6, 0x80000
	s_bfe_u32 s0, s0, 0x3000c
	s_add_i32 s9, s6, s0
	s_bfe_i32 s0, s9, 0x80000
	s_and_b32 s9, s9, 0xf8
	s_sub_i32 s6, s6, s9
	s_lshl_b32 s7, s7, 3
	s_sext_i32_i16 s0, s0
	s_sext_i32_i8 s6, s6
	s_lshr_b32 s1, s12, 8
	s_lshr_b32 s0, s0, 3
	s_add_i32 s70, s7, s6
	s_lshr_b32 s8, s12, 6
	s_ashr_i32 s71, s70, 31
	s_bfe_i64 s[10:11], s[0:1], 0x100000
	s_lshl_b32 s28, s8, 10
	s_lshl_b64 s[6:7], s[70:71], 21
	s_lshl_b64 s[10:11], s[10:11], 21
	v_readlane_b32 s14, v255, 15
	v_readlane_b32 s15, v255, 16
	s_add_u32 s48, s14, s10
	s_addc_u32 s49, s15, s11
	s_add_i32 s29, s28, 0
	v_and_b32_e32 v9, 0x60, v9
	s_add_i32 m0, s29, 0x10000
	v_or_b32_e32 v12, v12, v9
	global_load_lds_dwordx4 v136, s[48:49]
	s_add_i32 m0, s29, 0x12000
	v_lshl_or_b32 v140, v12, 7, v11
	s_add_u32 s10, s48, 0x4000
	global_load_lds_dwordx4 v140, s[48:49]
	s_addc_u32 s11, s49, 0
	s_add_i32 m0, s29, 0x14000
	v_lshl_or_b32 v138, v13, 7, v11
	global_load_lds_dwordx4 v136, s[10:11]
	s_add_i32 m0, s29, 0x16000
	s_add_u32 s50, s18, s6
	s_addc_u32 s51, s19, s7
	s_add_i32 s30, s29, 0x2000
	global_load_lds_dwordx4 v140, s[10:11]
	s_mov_b32 m0, s29
	s_add_u32 s6, s50, 0x4000
	global_load_lds_dwordx4 v134, s[50:51]
	s_mov_b32 m0, s30
	s_addc_u32 s7, s51, 0
	s_add_i32 s31, s29, 0x4000
	global_load_lds_dwordx4 v138, s[50:51]
	s_mov_b32 m0, s31
	s_add_i32 s35, s29, 0x6000
	global_load_lds_dwordx4 v134, s[6:7]
	s_mov_b32 m0, s35
	s_waitcnt vmcnt(0)
	v_mov_b32_e32 v143, 0
	global_load_lds_dwordx4 v138, s[6:7]
	s_cmp_eq_u32 s1, 1
	s_mov_b32 s57, 0
	v_mov_b32_e32 v137, v143
	v_mov_b32_e32 v141, v143
	v_mov_b32_e32 v135, v143
	v_mov_b32_e32 v139, v143
	s_cselect_b64 s[6:7], -1, 0
	s_cmp_lg_u32 s1, 1
	s_movk_i32 s61, 0x6000
	s_cbranch_scc1 .LBB0_672
	s_setprio 1
	s_barrier

;     __device__ __forceinline__ bool next(int i, Unit& u) const { if (i >= 2) return false; const int xcd = c & 7, off = c >> 3; u.pm = 16 * i + 4 * (xcd >> 1) + (off & 3); u.pn = 8 * (xcd & 1) + (off >> 2); return true; }
; #define PG8_STAGE(bufoff, gbase, voff) do { _Pragma("unroll") for (int _i = 0; _i < 2; ++_i) \
;         __builtin_amdgcn_global_load_lds((const unsigned*)((const char*)(gbase) + (voff)[_i]), (PG8_LAS unsigned*)(lds + (bufoff) + ldsw + _i * 8192), 16, 0, 0); } while (0)
; #define PG8_BAR __builtin_amdgcn_s_barrier()
; template <class Epi, class Sched, bool ALIGN_EPI = false, bool SP2 = false>
; __device__ __forceinline__ void gemm_phase(PG8_LAS unsigned char* lds, const Gemm g, const Sched& S, const Epi& E) {
;     ...
;     for (int i = 0; i < 2; ++i) { int R, C; stage_rc(tid * 16 + i * 8192, R, C); const int Rb = Epi::PERM ? ((R & ~31) + perm32(R & 31)) : R;
;         voffA[i] = (unsigned)(R * 64 + C) * 2u; voffB[i] = (unsigned)(Rb * 64 + C) * 2u; }
;     const size_t kstep = (size_t)(BM * BK * 2);
;     const size_t hstep = (size_t)HALF * BK * 2;
;     const size_t tstep = (size_t)K * BM * 2;
;     const unsigned ldsw = (unsigned)wid * 1024u;
;     const int aoff = lds_byte(wr * 64 + fr, fq * 8), boff = lds_byte(wc * 32 + fr, fq * 8);
;     ...
;     Unit cur, nxt; int ui = 0;
;     if (!S.next(0, cur)) return;
;     f32x4 acc[2][2][4][2];
; #pragma unroll
;     for (int a = 0; a < 2; ++a)
; #pragma unroll
;         for (int b = 0; b < 2; ++b)
; #pragma unroll
;             for (int m = 0; m < 4; ++m)
; #pragma unroll
;                 for (int n = 0; n < 2; ++n) acc[a][b][m][n] = (f32x4){0.f, 0.f, 0.f, 0.f};
;     bf16x8 At[4][2], B0[2][2], B1[2][2];
;     const char* cA = (const char*)g.A + (size_t)cur.pm * tstep; const char* cB = (const char*)g.Bt + (size_t)cur.pn * tstep;
;     S.a_ready(cur);
;     if constexpr (SP2) {
;         PG8_STAGE(PG8_SB(0, 0), cB, voffB); PG8_STAGE(PG8_SB(0, 1), cB + hstep, voffB); PG8_STAGE(PG8_SA(0, 0), cA, voffA); PG8_STAGE(PG8_SA(0, 1), cA + hstep, voffA);
;         if (wr == 1) PG8_BAR;
.LBB0_744:
	s_andn2_b64 vcc, exec, s[0:1]
	s_cbranch_vccnz .LBB0_780
	v_lshrrev_b32_e32 v7, 5, v0
	v_lshlrev_b32_e32 v4, 4, v0
	v_and_b32_e32 v1, 32, v0
	v_and_b32_e32 v6, 24, v196
	v_and_b32_e32 v7, 4, v7
	v_bfe_u32 v8, v0, 2, 2
	v_bfe_u32 v5, v0, 2, 4
	v_bitop3_b32 v2, v4, v1, 48 bitop3:0x6c
	s_waitcnt lgkmcnt(0)
	v_and_b32_e32 v3, 64, v0
	v_or3_b32 v7, v7, v8, v6
	v_lshrrev_b32_e32 v6, 3, v0
	v_or_b32_e32 v1, v2, v3
	v_and_or_b32 v8, v6, 48, v5
	v_and_or_b32 v6, v6, 32, v7
	s_waitcnt vmcnt(17)
	v_lshl_or_b32 v132, v6, 7, v1
	v_or_b32_e32 v6, 0x2000, v4
	v_lshl_or_b32 v130, v8, 7, v1
	v_lshrrev_b32_e32 v8, 7, v6
	s_movk_i32 s0, 0x70
	v_and_or_b32 v9, v8, s0, v5
	s_movk_i32 s0, 0x60
	v_and_or_b32 v7, v8, s0, v7
	s_lshr_b32 s0, s4, 6
	s_ashr_i32 s41, s40, 31
	s_ashr_i32 s39, s38, 31
	s_lshr_b32 s1, s4, 8
	s_lshl_b32 s3, s0, 10
	s_lshl_b64 s[8:9], s[40:41], 21
	s_lshl_b64 s[10:11], s[38:39], 21
	v_readlane_b32 s12, v255, 17
	v_readlane_b32 s13, v255, 18
	s_add_u32 s46, s12, s10
	s_addc_u32 s47, s13, s11
	s_add_i32 s26, s3, 0
	s_add_i32 m0, s26, 0x10000
	v_lshl_or_b32 v136, v7, 7, v1
	global_load_lds_dwordx4 v132, s[46:47]
	s_add_i32 m0, s26, 0x12000
	s_add_u32 s10, s46, 0x4000
	global_load_lds_dwordx4 v136, s[46:47]
	s_addc_u32 s11, s47, 0
	s_add_i32 m0, s26, 0x14000
	v_lshl_or_b32 v134, v9, 7, v1
	global_load_lds_dwordx4 v132, s[10:11]
	s_add_i32 m0, s26, 0x16000
	s_add_u32 s44, s66, s8
	s_addc_u32 s45, s67, s9
	s_add_i32 s27, s26, 0x2000
	global_load_lds_dwordx4 v136, s[10:11]
	s_mov_b32 m0, s26
	s_add_u32 s8, s44, 0x4000
	global_load_lds_dwordx4 v130, s[44:45]
	s_mov_b32 m0, s27
	s_addc_u32 s9, s45, 0
	s_add_i32 s28, s26, 0x4000
	global_load_lds_dwordx4 v134, s[44:45]
	s_mov_b32 m0, s28
	s_add_i32 s29, s26, 0x6000
	global_load_lds_dwordx4 v130, s[8:9]
	s_mov_b32 m0, s29
	v_mov_b32_e32 v133, 0
	global_load_lds_dwordx4 v134, s[8:9]
	s_cmp_eq_u32 s1, 1
	v_mov_b32_e32 v137, v133
	v_mov_b32_e32 v131, v133
	v_mov_b32_e32 v135, v133
	s_cselect_b64 s[8:9], -1, 0
	s_cmp_lg_u32 s1, 1
	s_mov_b32 s30, 0
	s_cbranch_scc1 .LBB0_747
	s_setprio 1
	s_barrier

; #define PG8_BAR __builtin_amdgcn_s_barrier()
;     __host__ __device__ bool next(int i, Unit& u) const {
;         const long L = (long)i * G + c; if (L >= nwg) return false;
;         int wgid = (int)L; { const int q = nwg / NXCD, r = nwg % NXCD, xcd = wgid % NXCD, off = wgid / NXCD; wgid = (xcd < r ? xcd * (q + 1) : r * (q + 1) + (xcd - r) * q) + off; }
;         const int nig = WGM * nN, gid = wgid / nig, fm = gid * WGM, gsz = (nM - fm) < WGM ? (nM - fm) : WGM;
;         u.pm = fm + ((wgid % nig) % gsz); u.pn = (wgid % nig) / gsz; return true;
; template <class Epi, class Sched, bool ALIGN_EPI = false, bool SP2 = false>
; __device__ __forceinline__ void gemm_phase(PG8_LAS unsigned char* lds, const Gemm g, const Sched& S, const Epi& E) {
;     const int tid = threadIdx.x, wid = __builtin_amdgcn_readfirstlane(tid >> 6), lane = tid & 63, wr = wid >> 2, wc = wid & 3, fr = lane & 15, fq = lane >> 4;
;     const int K = g.K, nt = K / BK;
;     unsigned voffA[2], voffB[2];
; #pragma unroll
;     for (int i = 0; i < 2; ++i) { int R, C; stage_rc(tid * 16 + i * 8192, R, C); const int Rb = Epi::PERM ? ((R & ~31) + perm32(R & 31)) : R;
;         voffA[i] = (unsigned)(R * 64 + C) * 2u; voffB[i] = (unsigned)(Rb * 64 + C) * 2u; }
;     const size_t kstep = (size_t)(BM * BK * 2);
;     const size_t hstep = (size_t)HALF * BK * 2;
;     const size_t tstep = (size_t)K * BM * 2;
;     const unsigned ldsw = (unsigned)wid * 1024u;
;     const int aoff = lds_byte(wr * 64 + fr, fq * 8), boff = lds_byte(wc * 32 + fr, fq * 8);
;     ...
;     Unit cur, nxt; int ui = 0;
;     if (!S.next(0, cur)) return;
;     f32x4 acc[2][2][4][2];
; #pragma unroll
;     for (int a = 0; a < 2; ++a)
; #pragma unroll
;         for (int b = 0; b < 2; ++b)
; #pragma unroll
;             for (int m = 0; m < 4; ++m)
; #pragma unroll
;                 for (int n = 0; n < 2; ++n) acc[a][b][m][n] = (f32x4){0.f, 0.f, 0.f, 0.f};
;     bf16x8 At[4][2], B0[2][2], B1[2][2];
;     const char* cA = (const char*)g.A + (size_t)cur.pm * tstep; const char* cB = (const char*)g.Bt + (size_t)cur.pn * tstep;
;     S.a_ready(cur);
;     if constexpr (SP2) {
;         PG8_STAGE(PG8_SB(0, 0), cB, voffB); PG8_STAGE(PG8_SB(0, 1), cB + hstep, voffB); PG8_STAGE(PG8_SA(0, 0), cA, voffA); PG8_STAGE(PG8_SA(0, 1), cA + hstep, voffA);
;         if (wr == 1) PG8_BAR;
.LBB0_830:
	s_add_u32 s6, s52, 0x1d600000
	s_addc_u32 s7, s53, 0
	s_cmp_lt_i32 s54, 12
	s_cselect_b64 s[0:1], -1, 0
	s_cmp_gt_i32 s55, 11
	s_cselect_b64 s[4:5], -1, 0
	s_and_b64 s[8:9], s[0:1], s[4:5]
	s_andn2_b64 vcc, exec, s[8:9]
	s_cbranch_vccnz .LBB0_855
	s_cmpk_gt_i32 s2, 0xabf
	v_readfirstlane_b32 s1, v0
	s_cbranch_scc1 .LBB0_847
	v_lshrrev_b32_e32 v7, 5, v0
	v_lshlrev_b32_e32 v4, 4, v0
	v_and_b32_e32 v1, 32, v0
	v_and_b32_e32 v6, 24, v196
	v_and_b32_e32 v7, 4, v7
	v_bfe_u32 v8, v0, 2, 2
	v_bfe_u32 v5, v0, 2, 4
	v_bitop3_b32 v2, v4, v1, 48 bitop3:0x6c
	s_waitcnt lgkmcnt(0)
	v_and_b32_e32 v3, 64, v0
	v_or3_b32 v8, v7, v8, v6
	v_lshrrev_b32_e32 v7, 3, v0
	v_or_b32_e32 v1, v2, v3
	v_and_or_b32 v9, v7, 48, v5
	v_and_or_b32 v7, v7, 32, v8
	s_waitcnt vmcnt(17)
	v_lshl_or_b32 v132, v7, 7, v1
	v_or_b32_e32 v7, 0x2000, v4
	v_lshl_or_b32 v130, v9, 7, v1
	v_lshrrev_b32_e32 v9, 7, v7
	s_movk_i32 s0, 0x70
	v_and_or_b32 v10, v9, s0, v5
	s_movk_i32 s0, 0x60
	s_ashr_i32 s26, s2, 31
	v_and_or_b32 v8, v9, s0, v8
	s_lshr_b32 s0, s26, 29
	s_add_i32 s0, s2, s0
	s_lshr_b32 s14, s1, 6
	s_ashr_i32 s4, s0, 3
	s_and_b32 s0, s0, -8
	s_lshr_b32 s15, s1, 8
	s_lshl_b32 s3, s14, 10
	s_sub_i32 s0, s2, s0
	s_cmp_lt_i32 s0, 0
	s_movk_i32 s27, 0x159
	s_cselect_b32 s5, s27, 0x158
	s_mul_i32 s0, s0, s5
	s_add_i32 s0, s0, s4
	s_mul_hi_i32 s4, s0, 0x2fa0be83
	s_lshr_b32 s5, s4, 31
	s_ashr_i32 s4, s4, 7
	s_add_i32 s4, s4, s5
	s_lshl_b32 s5, s4, 3
	s_mulk_i32 s4, 0x2b0
	s_sub_i32 s4, s0, s4
	s_sext_i32_i16 s0, s4
	s_bfe_u32 s0, s0, 0x3001c
	s_add_i32 s10, s4, s0
	s_sext_i32_i16 s0, s10
	s_and_b32 s10, s10, 0xfff8
	s_sub_i32 s4, s4, s10
	s_sext_i32_i16 s4, s4
	s_lshr_b32 s0, s0, 3
	s_add_i32 s4, s5, s4
	s_ashr_i32 s5, s4, 31
	s_bfe_i64 s[12:13], s[0:1], 0x100000
	s_lshl_b64 s[10:11], s[4:5], 21
	s_lshl_b64 s[12:13], s[12:13], 21
	v_readlane_b32 s5, v255, 13
	s_add_u32 s42, s5, s12
	v_readlane_b32 s5, v255, 14
	s_addc_u32 s43, s5, s13
	s_add_i32 s28, s3, 0
	s_add_i32 m0, s28, 0x10000
	v_lshl_or_b32 v136, v8, 7, v1
	global_load_lds_dwordx4 v132, s[42:43]
	s_add_i32 m0, s28, 0x12000
	s_add_u32 s12, s42, 0x4000
	global_load_lds_dwordx4 v136, s[42:43]
	s_addc_u32 s13, s43, 0
	s_add_i32 m0, s28, 0x14000
	v_lshl_or_b32 v134, v10, 7, v1
	global_load_lds_dwordx4 v132, s[12:13]
	s_add_i32 m0, s28, 0x16000
	s_add_u32 s40, s18, s10
	s_addc_u32 s41, s19, s11
	s_add_i32 s29, s28, 0x2000
	global_load_lds_dwordx4 v136, s[12:13]
	s_mov_b32 m0, s28
	s_add_u32 s10, s40, 0x4000
	global_load_lds_dwordx4 v130, s[40:41]
	s_mov_b32 m0, s29
	s_addc_u32 s11, s41, 0
	s_add_i32 s30, s28, 0x4000
	global_load_lds_dwordx4 v134, s[40:41]
	s_mov_b32 m0, s30
	s_add_i32 s31, s28, 0x6000
	global_load_lds_dwordx4 v130, s[10:11]
	s_mov_b32 m0, s31
	v_mov_b32_e32 v139, 0
	global_load_lds_dwordx4 v134, s[10:11]
	s_cmp_eq_u32 s15, 1
	v_mov_b32_e32 v133, v139
	v_mov_b32_e32 v137, v139
	v_mov_b32_e32 v131, v139
	v_mov_b32_e32 v135, v139
	s_cselect_b64 s[10:11], -1, 0
	s_cmp_lg_u32 s15, 1
	s_mov_b32 s33, 0
	s_cbranch_scc1 .LBB0_834
	s_setprio 1
	s_barrier

; #define PG8_BAR __builtin_amdgcn_s_barrier()
;     __host__ __device__ bool next(int i, Unit& u) const {
;         const long L = (long)i * G + c; if (L >= nwg) return false;
;         int wgid = (int)L; { const int q = nwg / NXCD, r = nwg % NXCD, xcd = wgid % NXCD, off = wgid / NXCD; wgid = (xcd < r ? xcd * (q + 1) : r * (q + 1) + (xcd - r) * q) + off; }
;         const int nig = WGM * nN, gid = wgid / nig, fm = gid * WGM, gsz = (nM - fm) < WGM ? (nM - fm) : WGM;
;         u.pm = fm + ((wgid % nig) % gsz); u.pn = (wgid % nig) / gsz; return true;
; template <class Epi, class Sched, bool ALIGN_EPI = false, bool SP2 = false>
; __device__ __forceinline__ void gemm_phase(PG8_LAS unsigned char* lds, const Gemm g, const Sched& S, const Epi& E) {
;     const int tid = threadIdx.x, wid = __builtin_amdgcn_readfirstlane(tid >> 6), lane = tid & 63, wr = wid >> 2, wc = wid & 3, fr = lane & 15, fq = lane >> 4;
;     const int K = g.K, nt = K / BK;
;     unsigned voffA[2], voffB[2];
; #pragma unroll
;     for (int i = 0; i < 2; ++i) { int R, C; stage_rc(tid * 16 + i * 8192, R, C); const int Rb = Epi::PERM ? ((R & ~31) + perm32(R & 31)) : R;
;         voffA[i] = (unsigned)(R * 64 + C) * 2u; voffB[i] = (unsigned)(Rb * 64 + C) * 2u; }
;     const size_t kstep = (size_t)(BM * BK * 2);
;     const size_t hstep = (size_t)HALF * BK * 2;
;     const size_t tstep = (size_t)K * BM * 2;
;     const unsigned ldsw = (unsigned)wid * 1024u;
;     const int aoff = lds_byte(wr * 64 + fr, fq * 8), boff = lds_byte(wc * 32 + fr, fq * 8);
;     ...
;     Unit cur, nxt; int ui = 0;
;     if (!S.next(0, cur)) return;
;     f32x4 acc[2][2][4][2];
; #pragma unroll
;     for (int a = 0; a < 2; ++a)
; #pragma unroll
;         for (int b = 0; b < 2; ++b)
; #pragma unroll
;             for (int m = 0; m < 4; ++m)
; #pragma unroll
;                 for (int n = 0; n < 2; ++n) acc[a][b][m][n] = (f32x4){0.f, 0.f, 0.f, 0.f};
;     bf16x8 At[4][2], B0[2][2], B1[2][2];
;     const char* cA = (const char*)g.A + (size_t)cur.pm * tstep; const char* cB = (const char*)g.Bt + (size_t)cur.pn * tstep;
;     S.a_ready(cur);
;     if constexpr (SP2) {
;         PG8_STAGE(PG8_SB(0, 0), cB, voffB); PG8_STAGE(PG8_SB(0, 1), cB + hstep, voffB); PG8_STAGE(PG8_SA(0, 0), cA, voffA); PG8_STAGE(PG8_SA(0, 1), cA + hstep, voffA);
;         if (wr == 1) PG8_BAR;
.LBB0_905:
	s_cmp_lt_i32 s54, 13
	s_cselect_b64 s[14:15], -1, 0
	s_cmpk_eq_i32 s60, 0x100
	s_cselect_b64 s[4:5], -1, 0
	s_and_b64 s[4:5], s[4:5], s[14:15]
	s_cmp_gt_i32 s55, 13
	s_cselect_b64 s[8:9], -1, 0
	s_and_b64 s[10:11], s[4:5], s[8:9]
	s_and_b64 s[0:1], s[14:15], s[0:1]
	s_mov_b64 s[4:5], -1
	s_xor_b64 s[12:13], s[10:11], -1
	s_andn2_b64 vcc, exec, s[0:1]
	s_mov_b64 s[0:1], 0
	s_cbranch_vccnz .LBB0_996
	v_lshlrev_b32_e32 v4, 4, v0
	v_and_b32_e32 v1, 32, v0
	v_lshrrev_b32_e32 v6, 5, v0
	v_bitop3_b32 v2, v4, v1, 48 bitop3:0x6c
	v_and_b32_e32 v1, 24, v196
	v_and_b32_e32 v6, 4, v6
	v_bfe_u32 v8, v0, 2, 2
	v_bfe_u32 v5, v0, 2, 4
	s_waitcnt lgkmcnt(0)
	v_and_b32_e32 v3, 64, v0
	v_or3_b32 v8, v6, v8, v1
	v_lshrrev_b32_e32 v6, 3, v0
	v_or_b32_e32 v7, v2, v3
	v_and_or_b32 v9, v6, 48, v5
	v_and_or_b32 v6, v6, 32, v8
	s_waitcnt vmcnt(17)
	v_lshl_or_b32 v132, v6, 7, v7
	v_or_b32_e32 v6, 0x2000, v4
	v_lshl_or_b32 v130, v9, 7, v7
	v_lshrrev_b32_e32 v9, 7, v6
	s_movk_i32 s0, 0x70
	v_and_or_b32 v10, v9, s0, v5
	s_movk_i32 s0, 0x60
	v_and_or_b32 v8, v9, s0, v8
	v_mov_b32_e32 v133, 0
	v_lshl_or_b32 v134, v10, 7, v7
	v_lshl_or_b32 v136, v8, 7, v7
	v_mov_b32_e32 v137, v133
	v_mov_b32_e32 v131, v133
	v_mov_b32_e32 v135, v133
	s_and_b64 vcc, exec, s[12:13]
	s_cbranch_vccz .LBB0_932
	s_cmpk_gt_i32 s2, 0x1ff
	v_readfirstlane_b32 s0, v0
	s_cbranch_scc1 .LBB0_931
	s_ashr_i32 s28, s2, 31
	s_lshr_b32 s1, s28, 29
	s_add_i32 s1, s2, s1
	s_ashr_i32 s14, s1, 3
	s_and_b32 s1, s1, -8
	s_lshr_b32 s4, s0, 6
	s_sub_i32 s1, s2, s1
	s_lshr_b32 s5, s0, 8
	s_lshl_b32 s3, s4, 10
	s_lshl_b32 s15, s1, 6
	s_cmp_lt_i32 s1, 0
	s_mulk_i32 s1, 0x41
	s_cselect_b32 s1, s1, s15
	s_add_i32 s1, s1, s14
	s_ashr_i32 s14, s1, 31
	s_lshr_b32 s14, s14, 25
	s_add_i32 s14, s1, s14
	s_ashr_i32 s15, s14, 7
	s_and_b32 s14, s14, 0xff80
	s_sub_i32 s14, s1, s14
	s_bfe_i32 s1, s14, 0x80000
	s_bfe_u32 s1, s1, 0x3000c
	s_add_i32 s16, s14, s1
	s_bfe_i32 s1, s16, 0x80000
	s_and_b32 s16, s16, 0xf8
	s_sub_i32 s14, s14, s16
	s_lshl_b32 s15, s15, 3
	s_sext_i32_i16 s17, s1
	s_sext_i32_i8 s14, s14
	s_add_i32 s59, s15, s14
	s_ashr_i32 s14, s17, 3
	s_lshr_b32 s1, s17, 3
	s_mul_hi_i32 s15, s14, 0x560000
	s_mul_i32 s14, s14, 0x560000
	s_add_u32 s36, s6, s14
	s_addc_u32 s37, s7, s15
	s_add_i32 s29, s3, 0
	s_add_i32 m0, s29, 0x10000
	v_lshl_add_u64 v[8:9], s[36:37], 0, v[132:133]
	global_load_lds_dwordx4 v[8:9], off
	s_add_i32 m0, s29, 0x12000
	s_add_u32 s14, s36, 0x4000
	v_lshl_add_u64 v[8:9], s[36:37], 0, v[136:137]
	s_addc_u32 s15, s37, 0
	global_load_lds_dwordx4 v[8:9], off
	s_add_i32 m0, s29, 0x14000
	v_lshl_add_u64 v[8:9], s[14:15], 0, v[132:133]
	s_mul_i32 s22, s59, 0x560000
	global_load_lds_dwordx4 v[8:9], off
	s_add_i32 m0, s29, 0x16000
	s_mul_hi_i32 s16, s59, 0x560000
	s_add_u32 s26, s20, s22
	v_lshl_add_u64 v[8:9], s[14:15], 0, v[136:137]
	s_addc_u32 s27, s21, s16
	s_add_i32 s30, s29, 0x2000
	global_load_lds_dwordx4 v[8:9], off
	v_lshl_add_u64 v[8:9], s[26:27], 0, v[130:131]
	s_mov_b32 m0, s29
	s_add_u32 s14, s26, 0x4000
	global_load_lds_dwordx4 v[8:9], off
	v_lshl_add_u64 v[8:9], s[26:27], 0, v[134:135]
	s_mov_b32 m0, s30
	s_addc_u32 s15, s27, 0
	s_add_i32 s31, s29, 0x4000
	global_load_lds_dwordx4 v[8:9], off
	v_lshl_add_u64 v[8:9], s[14:15], 0, v[130:131]
	s_mov_b32 m0, s31
	s_add_i32 s33, s29, 0x6000
	global_load_lds_dwordx4 v[8:9], off
	v_lshl_add_u64 v[8:9], s[14:15], 0, v[134:135]
	s_mov_b32 m0, s33
	s_cmp_eq_u32 s5, 1
	global_load_lds_dwordx4 v[8:9], off
	s_cselect_b64 s[14:15], -1, 0
	s_cmp_lg_u32 s5, 1
	s_mov_b32 s35, 0
	s_cbranch_scc1 .LBB0_910
	s_setprio 1
	s_barrier

;     __device__ __forceinline__ bool next(int i, Unit& u) const { if (i >= 2) return false; const int xcd = c & 7, off = c >> 3; u.pm = 16 * i + 4 * (xcd >> 1) + (off & 3); u.pn = 8 * (xcd & 1) + (off >> 2); return true; }
; #define PG8_STAGE(bufoff, gbase, voff) do { _Pragma("unroll") for (int _i = 0; _i < 2; ++_i) \
;         __builtin_amdgcn_global_load_lds((const unsigned*)((const char*)(gbase) + (voff)[_i]), (PG8_LAS unsigned*)(lds + (bufoff) + ldsw + _i * 8192), 16, 0, 0); } while (0)
; #define PG8_BAR __builtin_amdgcn_s_barrier()
; template <class Epi, class Sched, bool ALIGN_EPI = false, bool SP2 = false>
; __device__ __forceinline__ void gemm_phase(PG8_LAS unsigned char* lds, const Gemm g, const Sched& S, const Epi& E) {
;     const int tid = threadIdx.x, wid = __builtin_amdgcn_readfirstlane(tid >> 6), lane = tid & 63, wr = wid >> 2, wc = wid & 3, fr = lane & 15, fq = lane >> 4;
;     const int K = g.K, nt = K / BK;
;     unsigned voffA[2], voffB[2];
; #pragma unroll
;     for (int i = 0; i < 2; ++i) { int R, C; stage_rc(tid * 16 + i * 8192, R, C); const int Rb = Epi::PERM ? ((R & ~31) + perm32(R & 31)) : R;
;         voffA[i] = (unsigned)(R * 64 + C) * 2u; voffB[i] = (unsigned)(Rb * 64 + C) * 2u; }
;     const size_t kstep = (size_t)(BM * BK * 2);
;     const size_t hstep = (size_t)HALF * BK * 2;
;     const size_t tstep = (size_t)K * BM * 2;
;     const unsigned ldsw = (unsigned)wid * 1024u;
;     const int aoff = lds_byte(wr * 64 + fr, fq * 8), boff = lds_byte(wc * 32 + fr, fq * 8);
;     ...
;     Unit cur, nxt; int ui = 0;
;     if (!S.next(0, cur)) return;
;     f32x4 acc[2][2][4][2];
; #pragma unroll
;     for (int a = 0; a < 2; ++a)
; #pragma unroll
;         for (int b = 0; b < 2; ++b)
; #pragma unroll
;             for (int m = 0; m < 4; ++m)
; #pragma unroll
;                 for (int n = 0; n < 2; ++n) acc[a][b][m][n] = (f32x4){0.f, 0.f, 0.f, 0.f};
;     bf16x8 At[4][2], B0[2][2], B1[2][2];
;     const char* cA = (const char*)g.A + (size_t)cur.pm * tstep; const char* cB = (const char*)g.Bt + (size_t)cur.pn * tstep;
;     S.a_ready(cur);
;     if constexpr (SP2) {
;         PG8_STAGE(PG8_SB(0, 0), cB, voffB); PG8_STAGE(PG8_SB(0, 1), cB + hstep, voffB); PG8_STAGE(PG8_SA(0, 0), cA, voffA); PG8_STAGE(PG8_SA(0, 1), cA + hstep, voffA);
;         if (wr == 1) PG8_BAR;
.LBB0_932:
	s_andn2_b64 vcc, exec, s[4:5]
	s_cbranch_vccnz .LBB0_995
	s_lshl_b32 s0, s2, 1
	s_bfe_u32 s1, s2, 0x20003
	s_and_b32 s0, s0, 12
	s_or_b32 s28, s0, s1
	v_readlane_b32 s0, v255, 19
	s_ashr_i32 s2, s2, 5
	s_and_b32 s0, s0, 8
	s_add_i32 s8, s0, s2
	s_ashr_i32 s9, s8, 31
	s_mul_i32 s2, s8, 0x560000
	s_mul_hi_i32 s1, s8, 0x560000
	s_add_u32 s14, s6, s2
	s_mul_i32 s0, s28, 0x560000
	s_addc_u32 s15, s7, s1
	s_add_u32 s16, s20, s0
	s_addc_u32 s17, s21, 0
	s_add_u32 s0, s16, 0x4000
	s_addc_u32 s1, s17, 0
	v_lshl_add_u64 v[2:3], s[0:1], 0, v[134:135]
	v_lshl_add_u64 v[4:5], s[0:1], 0, v[130:131]
	s_add_u32 s0, s14, 0x4000
	s_addc_u32 s1, s15, 0
	v_readfirstlane_b32 s6, v0
	v_lshl_add_u64 v[10:11], s[0:1], 0, v[136:137]
	v_lshl_add_u64 v[12:13], s[0:1], 0, v[132:133]
	s_lshr_b32 s0, s6, 6
	s_lshl_b32 s29, s0, 10
	s_add_i32 s30, s29, 0
	v_lshl_add_u64 v[16:17], s[14:15], 0, v[132:133]
	s_add_i32 m0, s30, 0x10000
	v_lshl_add_u64 v[14:15], s[14:15], 0, v[136:137]
	global_load_lds_dwordx4 v[16:17], off
	s_add_i32 m0, s30, 0x12000
	v_lshl_add_u64 v[8:9], s[16:17], 0, v[130:131]
	global_load_lds_dwordx4 v[14:15], off
	s_add_i32 m0, s30, 0x14000
	s_add_i32 s31, s30, 0x2000
	global_load_lds_dwordx4 v[12:13], off
	s_add_i32 m0, s30, 0x16000
	v_lshl_add_u64 v[6:7], s[16:17], 0, v[134:135]
	global_load_lds_dwordx4 v[10:11], off
	s_mov_b32 m0, s30
	s_add_i32 s35, s30, 0x4000
	global_load_lds_dwordx4 v[8:9], off
	s_mov_b32 m0, s31
	s_add_i32 s48, s30, 0x6000
	global_load_lds_dwordx4 v[6:7], off
	s_mov_b32 m0, s35
	s_lshr_b32 s7, s6, 8
	global_load_lds_dwordx4 v[4:5], off
	s_mov_b32 m0, s48
	s_cmp_eq_u32 s7, 1
	global_load_lds_dwordx4 v[2:3], off
	s_cselect_b64 s[22:23], -1, 0
	s_cmp_lg_u32 s7, 1
	s_mov_b32 s25, 0
	s_cbranch_scc1 .LBB0_935
	s_setprio 1
	s_barrier
